# GEMM tile prologue: rowscale loads issued before the first STAGE loads, their wait/rsqrt deferred until after the 8 STAGE loads are in flight (counted vmcnt)
# speedup vs baseline: 1.0003x; 1.0003x over previous
; DI float shx_(float v, int m) { return __int_as_float(__builtin_amdgcn_ds_bpermute((lane_pinned_() ^ m) << 2, __float_as_int(v))); }
; DI int shx_(int v, int m) { return __builtin_amdgcn_ds_bpermute((lane_pinned_() ^ m) << 2, v); }
; DI void gemm_tile(const GD& g, int pm, int pn, bf16_t* shm) {
;     ...
;   if (g.rowscale) {
;     const int row = tid_ >> 1, hf = tid_ & 1;
;     const float4* pp = reinterpret_cast<const float4*>(g.ss + (long)(brow + row) * 32 + hf * 16);
;     const float4 a0 = pp[0], a1 = pp[1], a2 = pp[2], a3 = pp[3];
;     float ssum = (((a0.x + a0.y) + (a0.z + a0.w)) + ((a1.x + a1.y) + (a1.z + a1.w))) + (((a2.x + a2.y) + (a2.z + a2.w)) + ((a3.x + a3.y) + (a3.z + a3.w)));
;     ssum += shx_(ssum, 1);
;     if (hf == 0) rsc[row] = rsqrtf(ssum * (1.f / 2048.f) + EPS);
;   }
;   f32x4 acc[2][2][4][2] = {};
;   bf16x8 At[4][2], B0[2][2], B1[2][2];
;   const int nt = g.K / BK;
;   STAGE(SB(0, 0), Bt, ldb, bh0, 0); STAGE(SA(0, 0), A, lda, brow, 0);
;   STAGE(SB(0, 1), Bt, ldb, bh1, 0); STAGE(SA(0, 1), A, lda, brow + HALF, 0);
.LBB0_450:
	v_mov_b32_e32 v130, v204
	s_lshl_b32 s18, s27, 8
	s_cmp_lg_u32 s2, 0
	s_waitcnt vmcnt(0)
	v_ashrrev_i32_e32 v2, 6, v130
	s_mov_b32 s3, s77
	s_cselect_b64 s[30:31], -1, 0
	s_cmp_eq_u32 s2, 0
	v_readfirstlane_b32 s4, v2
	s_cbranch_scc1 .LBB0_454
	v_mov_b32_e32 v101, 0
	v_ashrrev_i32_e32 v103, 1, v130
	v_add_u32_e32 v104, s18, v103
	v_ashrrev_i32_e32 v105, 31, v104
	v_and_b32_e32 v120, 1, v130
	v_lshlrev_b64 v[104:105], 7, v[104:105]
	v_lshl_add_u64 v[104:105], s[42:43], 0, v[104:105]
	v_lshlrev_b32_e32 v100, 6, v120
	v_lshl_add_u64 v[116:117], v[104:105], 0, v[100:101]
	global_load_dwordx4 v[104:107], v[116:117], off
	global_load_dwordx4 v[108:111], v[116:117], off offset:16
	global_load_dwordx4 v[112:115], v[116:117], off offset:32
	s_nop 0
	global_load_dwordx4 v[116:119], v[116:117], off offset:48
.LBB0_454:
	s_waitcnt lgkmcnt(0)
	v_bfe_i32 v4, v130, 27, 1
	v_lshlrev_b32_e32 v0, 4, v130
	v_lshrrev_b32_e32 v4, 22, v4
	v_add_u32_e32 v4, v0, v4
	v_and_b32_e32 v4, 0xfffffc00, v4
	v_ashrrev_i32_e32 v3, 31, v130
	v_sub_u32_e32 v0, v0, v4
	v_lshrrev_b32_e32 v3, 26, v3
	v_lshrrev_b32_e32 v4, 4, v0
	v_add_u32_e32 v3, v130, v3
	v_bitop3_b32 v4, v4, v0, 32 bitop3:0x6c
	v_ashrrev_i32_e32 v0, 31, v0
	s_lshl_b32 s19, s49, 8
	s_lshl_b32 s72, s49, 7
	v_ashrrev_i32_e32 v3, 6, v3
	v_lshrrev_b32_e32 v0, 26, v0
	s_lshl_b32 s6, s4, 10
	s_add_i32 s7, s72, 0x1600
	s_or_b32 s9, s19, 0x80
	v_lshlrev_b32_e32 v5, 3, v3
	v_add_u32_e32 v0, v4, v0
	s_cmp_eq_u32 s48, 3
	v_and_b32_e32 v5, 0x7ffffff0, v5
	v_ashrrev_i32_e32 v6, 6, v0
	v_lshlrev_b32_e32 v0, 5, v3
	s_cselect_b64 s[4:5], -1, 0
	v_add_u32_e32 v5, v6, v5
	v_and_b32_e32 v0, 32, v0
	v_mul_i32_i24_e32 v3, 64, v6
	s_and_b64 s[2:3], s[4:5], exec
	v_sub_u32_e32 v3, v4, v3
	v_mad_u64_u32 v[4:5], s[2:3], v5, s8, v[0:1]
	s_cselect_b32 s12, s72, s19
	s_cselect_b32 s9, s7, s9
	s_ashr_i32 s2, s12, 31
	s_add_i32 s70, s6, 0
	s_mul_i32 s6, s2, s8
	s_mul_hi_u32 s2, s12, s8
	s_add_i32 s3, s2, s6
	s_mul_i32 s2, s12, s8
	s_mov_b32 s89, s36
	s_add_i32 s36, s70, 0x10000
	s_lshl_b64 s[10:11], s[2:3], 1
	s_mov_b64 s[22:23], s[60:61]
	s_add_u32 s60, s58, s10
	s_addc_u32 s61, s59, s11
	s_or_b32 s2, s12, 64
	s_mul_hi_u32 s3, s2, s8
	s_add_i32 s3, s3, s6
	s_mul_i32 s2, s2, s8
	s_lshl_b64 s[12:13], s[2:3], 1
	s_mov_b64 s[14:15], s[16:17]
	s_mov_b64 s[16:17], s[62:63]
	s_add_u32 s62, s58, s12
	s_mul_hi_u32 s3, s18, s8
	s_mul_i32 s2, s18, s8
	s_addc_u32 s63, s59, s13
	s_add_i32 s66, s70, 0x12000
	s_lshl_b64 s[50:51], s[2:3], 1
	s_add_u32 s24, s0, s50
	s_addc_u32 s25, s1, s51
	s_or_b32 s2, s18, 64
	s_mul_hi_u32 s3, s2, s8
	s_mul_i32 s2, s2, s8
	s_lshl_b64 s[52:53], s[2:3], 1
	s_add_u32 s2, s0, s52
	s_addc_u32 s3, s1, s53
	s_ashr_i32 s6, s9, 31
	s_mul_i32 s40, s6, s8
	s_mul_hi_u32 s6, s9, s8
	s_add_i32 s7, s6, s40
	s_mul_i32 s6, s9, s8
	s_add_i32 s44, s70, 0x2000
	s_add_i32 s69, s70, 0x14000
	s_lshl_b64 s[54:55], s[6:7], 1
	s_add_u32 s82, s58, s54
	s_addc_u32 s83, s59, s55
	s_or_b32 s6, s9, 64
	s_mul_hi_u32 s7, s6, s8
	s_add_i32 s7, s7, s40
	s_mul_i32 s6, s6, s8
	v_ashrrev_i16_sdwa v3, v207, sext(v3) dst_sel:DWORD dst_unused:UNUSED_PAD src0_sel:DWORD src1_sel:BYTE_0
	s_lshl_b64 s[56:57], s[6:7], 1
	v_bfe_i32 v3, v3, 0, 16
	s_add_u32 s40, s58, s56
	v_add_lshl_u32 v0, v4, v3, 1
	s_mov_b32 m0, s36
	s_addc_u32 s41, s59, s57
	s_or_b32 s6, s18, 0x80
	global_load_lds_dwordx4 v0, s[60:61]
	s_mov_b32 m0, s66
	s_mul_hi_u32 s7, s6, s8
	s_mul_i32 s6, s6, s8
	s_mov_b32 s88, s77
	global_load_lds_dwordx4 v0, s[62:63]
	s_mov_b32 m0, s70
	s_add_i32 s77, s70, 0x16000
	s_add_i32 s71, s70, 0x4000
	s_lshl_b64 s[6:7], s[6:7], 1
	s_mov_b32 s68, s96
	global_load_lds_dwordx4 v0, s[24:25]
	s_mov_b32 m0, s44
	s_add_u32 s96, s0, s6
	global_load_lds_dwordx4 v0, s[2:3]
	s_mov_b32 m0, s69
	s_addc_u32 s97, s1, s7
	s_or_b32 s65, s18, 0xc0
	global_load_lds_dwordx4 v0, s[82:83]
	s_mov_b32 m0, s77
	s_mul_hi_u32 s9, s65, s8
	s_mul_i32 s8, s65, s8
	global_load_lds_dwordx4 v0, s[40:41]
	s_mov_b32 m0, s71
	s_lshl_b64 s[8:9], s[8:9], 1
	global_load_lds_dwordx4 v0, s[96:97]
	s_add_u32 s96, s0, s8
	s_addc_u32 s97, s1, s9
	s_add_i32 s65, s70, 0x6000
	s_mov_b32 m0, s65
	v_ashrrev_i32_e32 v3, 8, v130
	global_load_lds_dwordx4 v0, s[96:97]
	s_andn2_b64 vcc, exec, s[30:31]
	s_cbranch_vccnz .Lrs_skip
	v_mov_b32_e32 v100, v208
	v_cmp_eq_u32_e32 vcc, 0, v120
	v_lshlrev_b32_e32 v121, 2, v100
	s_waitcnt vmcnt(11)
	v_add_f32_e32 v100, v104, v105
	v_add_f32_e32 v104, v106, v107
	s_waitcnt vmcnt(10)
	v_add_f32_e32 v105, v108, v109
	v_add_f32_e32 v106, v110, v111
	s_waitcnt vmcnt(9)
	v_add_f32_e32 v107, v112, v113
	v_add_f32_e32 v108, v114, v115
	s_waitcnt vmcnt(8)
	v_add_f32_e32 v109, v116, v117
	v_add_f32_e32 v110, v118, v119
	v_add_f32_e32 v100, v100, v104
	v_add_f32_e32 v104, v105, v106
	v_add_f32_e32 v105, v107, v108
	v_add_f32_e32 v106, v109, v110
	v_add_f32_e32 v100, v100, v104
	v_add_f32_e32 v104, v105, v106
	v_add_f32_e32 v100, v100, v104
	v_xor_b32_e32 v104, 4, v121
	ds_bpermute_b32 v104, v104, v100
	s_and_saveexec_b64 s[96:97], vcc
	s_cbranch_execz .Lrs_453
	s_waitcnt lgkmcnt(0)
	v_add_f32_e32 v100, v100, v104
	v_fmamk_f32 v100, v100, 0x3a000000, v205
	v_mul_f32_e32 v104, 0x4b800000, v100
	v_cmp_gt_f32_e32 vcc, s33, v100
	v_lshl_add_u32 v103, v103, 2, 0
	v_add_u32_e32 v103, 0x22000, v103
	v_cndmask_b32_e32 v100, v100, v104, vcc
	v_rsq_f32_e32 v100, v100
	s_nop 0
	v_mul_f32_e32 v104, 0x45800000, v100
	v_cndmask_b32_e32 v100, v100, v104, vcc
	ds_write_b32 v103, v100
.Lrs_453:
	s_or_b64 exec, exec, s[96:97]
	s_waitcnt lgkmcnt(0)
.Lrs_skip:
	v_cmp_eq_u32_e32 vcc, 1, v3
	s_and_saveexec_b64 s[96:97], vcc
	s_cbranch_execz .LBB0_456
	s_barrier
